# adds: P1 mod-slice loads (b_ada + 16 partials) issued before the shift/scale staging and summed after it, same order
# baseline (speedup 1.0000x reference)
.LBB0_104:
	s_cmp_lt_i32 s72, 2
	s_cselect_b64 s[0:1], -1, 0
	s_add_u32 s14, s70, 0x9b00000
	s_addc_u32 s15, s71, 0
	s_add_u32 s6, s70, 0x1d300000
	s_addc_u32 s7, s71, 0
	v_writelane_b32 v255, s6, 8
	s_and_b64 s[4:5], s[0:1], s[4:5]
	s_andn2_b64 vcc, exec, s[4:5]
	v_writelane_b32 v255, s7, 9
	s_cbranch_vccnz .LBB0_117
	s_abs_i32 s3, s74
	v_cvt_f32_u32_e32 v0, s3
	s_sub_i32 s0, 0, s3
	s_ashr_i32 s10, s74, 31
	s_mov_b32 s16, 0xc000
	v_rcp_iflag_f32_e32 v0, v0
	s_nop 0
	v_mul_f32_e32 v0, 0x4f7ffffe, v0
	v_cvt_u32_f32_e32 v0, v0
	s_nop 0
	v_readfirstlane_b32 s11, v0
	s_mul_i32 s0, s0, s11
	s_mul_hi_u32 s0, s11, s0
	s_add_i32 s11, s11, s0
	s_mul_hi_u32 s0, s11, 0xc000
	s_mul_i32 s1, s0, s3
	s_sub_i32 s1, 0xc000, s1
	s_add_i32 s6, s0, 1
	s_sub_i32 s7, s1, s3
	s_cmp_ge_u32 s1, s3
	s_cselect_b32 s0, s6, s0
	s_cselect_b32 s1, s7, s1
	s_add_i32 s6, s0, 1
	s_cmp_ge_u32 s1, s3
	s_cselect_b32 s0, s6, s0
	s_xor_b32 s0, s0, s10
	s_sub_i32 s17, s0, s10
	s_cmpk_gt_i32 s17, 0x200
	s_cbranch_scc1 .Lp1mod_old
	v_cmp_gt_i32_e32 vcc, s17, v252
	s_mov_b64 s[30:31], vcc
	s_and_saveexec_b64 s[0:1], vcc
	s_cbranch_execz .LBB0_110
	s_mul_i32 s18, s17, s2
	s_mov_b32 s19, 0x2aaaaaab
	v_add_u32_e32 v0, s18, v252
	v_mul_hi_i32 v1, v0, s19
	v_lshrrev_b32_e32 v2, 31, v1
	v_ashrrev_i32_e32 v1, 11, v1
	v_add_u32_e32 v1, v1, v2
	v_mul_i32_i24_e32 v2, 0x3000, v1
	v_sub_u32_e32 v2, v0, v2
	v_ashrrev_i32_e32 v3, 31, v2
	v_lshlrev_b64 v[2:3], 2, v[2:3]
	s_waitcnt lgkmcnt(0)
	v_lshl_add_u64 v[6:7], s[42:43], 0, v[2:3]
	global_load_dword v186, v[6:7], off
	v_mad_i64_i32 v[2:3], s[8:9], v1, s16, v[2:3]
	v_lshl_add_u64 v[2:3], s[70:71], 0, v[2:3]
	v_mov_b32_e32 v188, v0
	v_add_co_u32_e32 v6, vcc, 0x1d000000, v2
	s_nop 1
	v_addc_co_u32_e32 v7, vcc, 0, v3, vcc
	s_mov_b64 s[22:23], 0x30000
	global_load_dword v170, v[6:7], off
	v_lshl_add_u64 v[6:7], v[6:7], 0, s[22:23]
	global_load_dword v171, v[6:7], off
	v_lshl_add_u64 v[6:7], v[6:7], 0, s[22:23]
	global_load_dword v172, v[6:7], off
	v_lshl_add_u64 v[6:7], v[6:7], 0, s[22:23]
	global_load_dword v173, v[6:7], off
	v_lshl_add_u64 v[6:7], v[6:7], 0, s[22:23]
	global_load_dword v174, v[6:7], off
	v_lshl_add_u64 v[6:7], v[6:7], 0, s[22:23]
	global_load_dword v175, v[6:7], off
	v_lshl_add_u64 v[6:7], v[6:7], 0, s[22:23]
	global_load_dword v176, v[6:7], off
	v_lshl_add_u64 v[6:7], v[6:7], 0, s[22:23]
	global_load_dword v177, v[6:7], off
	v_lshl_add_u64 v[6:7], v[6:7], 0, s[22:23]
	global_load_dword v178, v[6:7], off
	v_lshl_add_u64 v[6:7], v[6:7], 0, s[22:23]
	global_load_dword v179, v[6:7], off
	v_lshl_add_u64 v[6:7], v[6:7], 0, s[22:23]
	global_load_dword v180, v[6:7], off
	v_lshl_add_u64 v[6:7], v[6:7], 0, s[22:23]
	global_load_dword v181, v[6:7], off
	v_lshl_add_u64 v[6:7], v[6:7], 0, s[22:23]
	global_load_dword v182, v[6:7], off
	v_lshl_add_u64 v[6:7], v[6:7], 0, s[22:23]
	global_load_dword v183, v[6:7], off
	v_lshl_add_u64 v[6:7], v[6:7], 0, s[22:23]
	global_load_dword v184, v[6:7], off
	v_lshl_add_u64 v[6:7], v[6:7], 0, s[22:23]
	global_load_dword v185, v[6:7], off
	s_branch .LBB0_110
.Lp1mod_old:
	s_mov_b64 s[30:31], 0
	v_cmp_gt_i32_e32 vcc, s17, v252
	s_and_saveexec_b64 s[0:1], vcc
	s_cbranch_execz .LBB0_110
	s_mul_i32 s18, s17, s2
	s_mov_b64 s[6:7], 0
	s_mov_b32 s19, 0x2aaaaaab
	v_mov_b32_e32 v4, v252

.LBB0_114:
	s_or_b64 exec, exec, s[8:9]
	s_and_saveexec_b64 s[26:27], s[30:31]
	s_cbranch_execz .Lp1mod_done
	s_waitcnt vmcnt(0)
	v_add_f32_e32 v186, v186, v170
	v_add_f32_e32 v186, v186, v171
	v_add_f32_e32 v186, v186, v172
	v_add_f32_e32 v186, v186, v173
	v_add_f32_e32 v186, v186, v174
	v_add_f32_e32 v186, v186, v175
	v_add_f32_e32 v186, v186, v176
	v_add_f32_e32 v186, v186, v177
	v_add_f32_e32 v186, v186, v178
	v_add_f32_e32 v186, v186, v179
	v_add_f32_e32 v186, v186, v180
	v_add_f32_e32 v186, v186, v181
	v_add_f32_e32 v186, v186, v182
	v_add_f32_e32 v186, v186, v183
	v_add_f32_e32 v186, v186, v184
	v_add_f32_e32 v186, v186, v185
	v_readlane_b32 s22, v255, 8
	v_readlane_b32 s23, v255, 9
	v_ashrrev_i32_e32 v189, 31, v188
	s_nop 2
	v_lshl_add_u64 v[188:189], v[188:189], 2, s[22:23]
	global_store_dword v[188:189], v186, off
.Lp1mod_done:
	s_or_b64 exec, exec, s[26:27]
	v_readlane_b32 s0, v255, 5
	s_cmp_ge_i32 s0, s3
	s_waitcnt lgkmcnt(0)
	s_barrier
	s_cbranch_scc1 .LBB0_117
	v_mov_b32_e32 v1, 0
	v_lshlrev_b32_e32 v2, 3, v222
	v_mov_b32_e32 v3, v1
	v_lshl_add_u64 v[26:27], s[14:15], 0, v[2:3]
	v_lshlrev_b32_e32 v2, 2, v222
	v_lshlrev_b32_e32 v0, 4, v222
	v_lshl_add_u64 v[2:3], s[70:71], 0, v[2:3]
	s_mov_b64 s[0:1], 0x1f800000
	v_lshl_add_u64 v[24:25], s[36:37], 0, v[0:1]
	v_lshl_add_u64 v[28:29], v[2:3], 0, s[0:1]
	v_add_u32_e32 v36, 0, v0
	s_movk_i32 s6, 0x1000
	s_movk_i32 s7, 0x2000
	s_movk_i32 s8, 0x3000
	v_mov_b32_e32 v37, 0x358637bd
	s_mov_b32 s9, 0xf800000
	v_mov_b32_e32 v38, 0x260
	s_mov_b32 s10, 0xc3e00000
	v_mov_b32_e32 v39, 0x43e00000
	v_readlane_b32 s11, v255, 5
	s_mov_b64 s[26:27], 0x1000
	s_mov_b64 s[30:31], 0x2000
	s_mov_b64 s[34:35], 0x3000
	s_add_i32 s23, s16, s11
	v_mov_b32_e32 v162, s23
	v_mov_b32_e32 v163, 0
	v_lshlrev_b64 v[162:163], 14, v[162:163]
	v_lshl_add_u64 v[160:161], v[162:163], 0, v[24:25]
	v_lshl_add_u64 v[164:165], v[160:161], 0, s[26:27]
	v_lshl_add_u64 v[166:167], v[160:161], 0, s[30:31]
	v_lshl_add_u64 v[168:169], v[160:161], 0, s[34:35]
	global_load_dwordx4 v[64:67], v[160:161], off nt
	global_load_dwordx4 v[68:71], v[160:161], off offset:1024 nt
	global_load_dwordx4 v[72:75], v[160:161], off offset:2048 nt
	global_load_dwordx4 v[76:79], v[160:161], off offset:3072 nt
	global_load_dwordx4 v[80:83], v[164:165], off nt
	global_load_dwordx4 v[84:87], v[164:165], off offset:1024 nt
	global_load_dwordx4 v[88:91], v[164:165], off offset:2048 nt
	global_load_dwordx4 v[92:95], v[164:165], off offset:3072 nt
	global_load_dwordx4 v[96:99], v[166:167], off nt
	global_load_dwordx4 v[100:103], v[166:167], off offset:1024 nt
	global_load_dwordx4 v[104:107], v[166:167], off offset:2048 nt
	global_load_dwordx4 v[108:111], v[166:167], off offset:3072 nt
	global_load_dwordx4 v[112:115], v[168:169], off nt
	global_load_dwordx4 v[116:119], v[168:169], off offset:1024 nt
	global_load_dwordx4 v[120:123], v[168:169], off offset:2048 nt
	global_load_dwordx4 v[124:127], v[168:169], off offset:3072 nt
